# EpiFfnUp epilogue hand-written: rstd/cf fetched from LDS once per unit instead of per block, packed-f32 FMA (bit-identical), saddr stores; both layers
# baseline (speedup 1.0000x reference)
; #define LAS __attribute__((address_space(3)))
; __device__ __forceinline__ pg8::u32x4 pack8(const f32x4 a, const f32x4 b) { pg8::u32x4 w; w.x = pg8::cvt_pk_bf16(a[0], a[1]); w.y = pg8::cvt_pk_bf16(a[2], a[3]); w.z = pg8::cvt_pk_bf16(b[0], b[1]); w.w = pg8::cvt_pk_bf16(b[2], b[3]); return w; }
; #define EPI_FOREACH(...) _Pragma("unroll") for (int ai = 0; ai < 2; ++ai) _Pragma("unroll") for (int m = 0; m < 4; ++m) _Pragma("unroll") for (int bj = 0; bj < 2; ++bj) { \
;         const int row = u.pm * 256 + ai * 128 + wr * 64 + m * 16 + fr, col = u.pn * 256 + bj * 128 + wc * 32 + 8 * fq; const f32x4 v0 = acc[ai][bj][m][0], v1 = acc[ai][bj][m][1]; (void)row; (void)col; __VA_ARGS__ }
;     __device__ __forceinline__ void operator()(const f32x4 (&acc)[2][2][4][2], const pg8::Unit& u, int wr, int wc, int fr, int fq, int par) const {
;         const LAS float* rp = red + par * 512 + wr * 64 + fr; const LAS float* cp = rp - (wr * 64 + fr) + 256 + wc * 32 + 8 * fq;
;         EPI_FOREACH( const f32x4 c0 = *(const LAS f32x4*)(cp + bj * 128), c1 = *(const LAS f32x4*)(cp + bj * 128 + 4); const float r = rp[ai * 128 + m * 16]; f32x4 a, b;
;             _Pragma("unroll") for (int q = 0; q < 4; ++q) { const float ra = fmaxf(v0[q] * r + c0[q], 0.f), rb = fmaxf(v1[q] * r + c1[q], 0.f); a[q] = ra * ra; b[q] = rb * rb; }
;             *(pg8::u32x4*)(O + (size_t)row * DFF + col) = pack8(a, b); )
;     }
.LBB0_1712:
	s_add_u32 s50, s47, 0xffffff00
	s_addc_u32 s51, s80, -1
	s_lshl_b32 s43, s78, 11
	s_and_b32 s43, s43, 0x800
	v_add_u32_e32 v226, s43, v161
	v_lshl_add_u32 v227, v160, 2, v226
	s_lshl_b32 s43, s66, 2
	v_lshlrev_b32_e32 v228, 2, v158
	v_add3_u32 v227, v227, s43, v228
	ds_read_b128 v[166:169], v227 offset:1024
	ds_read_b128 v[170:173], v227 offset:1040
	ds_read_b128 v[174:177], v227 offset:1536
	ds_read_b128 v[178:181], v227 offset:1552
	ds_read_b32 v182, v226
	ds_read_b32 v184, v226 offset:64
	ds_read_b32 v186, v226 offset:128
	ds_read_b32 v188, v226 offset:192
	ds_read_b32 v190, v226 offset:512
	ds_read_b32 v192, v226 offset:576
	ds_read_b32 v194, v226 offset:640
	ds_read_b32 v196, v226 offset:704
	v_lshl_add_u32 v229, s18, 8, v157
	v_lshlrev_b32_e32 v229, 13, v229
	v_lshl_or_b32 v228, s16, 8, v162
	v_lshl_add_u32 v229, v228, 1, v229
	s_mov_b64 s[98:99], s[24:25]
	s_waitcnt lgkmcnt(0)
	v_pk_fma_f32 v[198:199], v[6:7], v[182:183], v[166:167] op_sel_hi:[1,0,1]
	v_pk_fma_f32 v[200:201], v[8:9], v[182:183], v[168:169] op_sel_hi:[1,0,1]
	v_pk_fma_f32 v[202:203], v[130:131], v[182:183], v[170:171] op_sel_hi:[1,0,1]
	v_pk_fma_f32 v[204:205], v[132:133], v[182:183], v[172:173] op_sel_hi:[1,0,1]
	v_max_f32_e32 v198, 0, v198
	v_max_f32_e32 v199, 0, v199
	v_max_f32_e32 v200, 0, v200
	v_max_f32_e32 v201, 0, v201
	v_max_f32_e32 v202, 0, v202
	v_max_f32_e32 v203, 0, v203
	v_max_f32_e32 v204, 0, v204
	v_max_f32_e32 v205, 0, v205
	v_pk_mul_f32 v[198:199], v[198:199], v[198:199]
	v_pk_mul_f32 v[200:201], v[200:201], v[200:201]
	v_pk_mul_f32 v[202:203], v[202:203], v[202:203]
	v_pk_mul_f32 v[204:205], v[204:205], v[204:205]
	v_cvt_pk_bf16_f32 v214, v198, v199
	v_cvt_pk_bf16_f32 v215, v200, v201
	v_cvt_pk_bf16_f32 v216, v202, v203
	v_cvt_pk_bf16_f32 v217, v204, v205
	global_store_dwordx4 v229, v[214:217], s[98:99]
	v_pk_fma_f32 v[206:207], v[102:103], v[182:183], v[174:175] op_sel_hi:[1,0,1]
	v_pk_fma_f32 v[208:209], v[104:105], v[182:183], v[176:177] op_sel_hi:[1,0,1]
	v_pk_fma_f32 v[210:211], v[98:99], v[182:183], v[178:179] op_sel_hi:[1,0,1]
	v_pk_fma_f32 v[212:213], v[100:101], v[182:183], v[180:181] op_sel_hi:[1,0,1]
	v_max_f32_e32 v206, 0, v206
	v_max_f32_e32 v207, 0, v207
	v_max_f32_e32 v208, 0, v208
	v_max_f32_e32 v209, 0, v209
	v_max_f32_e32 v210, 0, v210
	v_max_f32_e32 v211, 0, v211
	v_max_f32_e32 v212, 0, v212
	v_max_f32_e32 v213, 0, v213
	v_pk_mul_f32 v[206:207], v[206:207], v[206:207]
	v_pk_mul_f32 v[208:209], v[208:209], v[208:209]
	v_pk_mul_f32 v[210:211], v[210:211], v[210:211]
	v_pk_mul_f32 v[212:213], v[212:213], v[212:213]
	v_cvt_pk_bf16_f32 v218, v206, v207
	v_cvt_pk_bf16_f32 v219, v208, v209
	v_cvt_pk_bf16_f32 v220, v210, v211
	v_cvt_pk_bf16_f32 v221, v212, v213
	global_store_dwordx4 v229, v[218:221], s[98:99] offset:256
	s_add_u32 s98, s98, 0x20000
	s_addc_u32 s99, s99, 0
	v_pk_fma_f32 v[198:199], v[126:127], v[184:185], v[166:167] op_sel_hi:[1,0,1]
	v_pk_fma_f32 v[200:201], v[128:129], v[184:185], v[168:169] op_sel_hi:[1,0,1]
	v_pk_fma_f32 v[202:203], v[122:123], v[184:185], v[170:171] op_sel_hi:[1,0,1]
	v_pk_fma_f32 v[204:205], v[124:125], v[184:185], v[172:173] op_sel_hi:[1,0,1]
	v_max_f32_e32 v198, 0, v198
	v_max_f32_e32 v199, 0, v199
	v_max_f32_e32 v200, 0, v200
	v_max_f32_e32 v201, 0, v201
	v_max_f32_e32 v202, 0, v202
	v_max_f32_e32 v203, 0, v203
	v_max_f32_e32 v204, 0, v204
	v_max_f32_e32 v205, 0, v205
	v_pk_mul_f32 v[198:199], v[198:199], v[198:199]
	v_pk_mul_f32 v[200:201], v[200:201], v[200:201]
	v_pk_mul_f32 v[202:203], v[202:203], v[202:203]
	v_pk_mul_f32 v[204:205], v[204:205], v[204:205]
	v_cvt_pk_bf16_f32 v222, v198, v199
	v_cvt_pk_bf16_f32 v223, v200, v201
	v_cvt_pk_bf16_f32 v224, v202, v203
	v_cvt_pk_bf16_f32 v225, v204, v205
	global_store_dwordx4 v229, v[222:225], s[98:99]
	v_pk_fma_f32 v[206:207], v[94:95], v[184:185], v[174:175] op_sel_hi:[1,0,1]
	v_pk_fma_f32 v[208:209], v[96:97], v[184:185], v[176:177] op_sel_hi:[1,0,1]
	v_pk_fma_f32 v[210:211], v[90:91], v[184:185], v[178:179] op_sel_hi:[1,0,1]
	v_pk_fma_f32 v[212:213], v[92:93], v[184:185], v[180:181] op_sel_hi:[1,0,1]
	v_max_f32_e32 v206, 0, v206
	v_max_f32_e32 v207, 0, v207
	v_max_f32_e32 v208, 0, v208
	v_max_f32_e32 v209, 0, v209
	v_max_f32_e32 v210, 0, v210
	v_max_f32_e32 v211, 0, v211
	v_max_f32_e32 v212, 0, v212
	v_max_f32_e32 v213, 0, v213
	v_pk_mul_f32 v[206:207], v[206:207], v[206:207]
	v_pk_mul_f32 v[208:209], v[208:209], v[208:209]
	v_pk_mul_f32 v[210:211], v[210:211], v[210:211]
	v_pk_mul_f32 v[212:213], v[212:213], v[212:213]
	v_cvt_pk_bf16_f32 v214, v206, v207
	v_cvt_pk_bf16_f32 v215, v208, v209
	v_cvt_pk_bf16_f32 v216, v210, v211
	v_cvt_pk_bf16_f32 v217, v212, v213
	global_store_dwordx4 v229, v[214:217], s[98:99] offset:256
	s_add_u32 s98, s98, 0x20000
	s_addc_u32 s99, s99, 0
	v_pk_fma_f32 v[198:199], v[118:119], v[186:187], v[166:167] op_sel_hi:[1,0,1]
	v_pk_fma_f32 v[200:201], v[120:121], v[186:187], v[168:169] op_sel_hi:[1,0,1]
	v_pk_fma_f32 v[202:203], v[114:115], v[186:187], v[170:171] op_sel_hi:[1,0,1]
	v_pk_fma_f32 v[204:205], v[116:117], v[186:187], v[172:173] op_sel_hi:[1,0,1]
	v_max_f32_e32 v198, 0, v198
	v_max_f32_e32 v199, 0, v199
	v_max_f32_e32 v200, 0, v200
	v_max_f32_e32 v201, 0, v201
	v_max_f32_e32 v202, 0, v202
	v_max_f32_e32 v203, 0, v203
	v_max_f32_e32 v204, 0, v204
	v_max_f32_e32 v205, 0, v205
	v_pk_mul_f32 v[198:199], v[198:199], v[198:199]
	v_pk_mul_f32 v[200:201], v[200:201], v[200:201]
	v_pk_mul_f32 v[202:203], v[202:203], v[202:203]
	v_pk_mul_f32 v[204:205], v[204:205], v[204:205]
	v_cvt_pk_bf16_f32 v218, v198, v199
	v_cvt_pk_bf16_f32 v219, v200, v201
	v_cvt_pk_bf16_f32 v220, v202, v203
	v_cvt_pk_bf16_f32 v221, v204, v205
; #define LAS __attribute__((address_space(3)))
; __device__ __forceinline__ pg8::u32x4 pack8(const f32x4 a, const f32x4 b) { pg8::u32x4 w; w.x = pg8::cvt_pk_bf16(a[0], a[1]); w.y = pg8::cvt_pk_bf16(a[2], a[3]); w.z = pg8::cvt_pk_bf16(b[0], b[1]); w.w = pg8::cvt_pk_bf16(b[2], b[3]); return w; }
; #define EPI_FOREACH(...) _Pragma("unroll") for (int ai = 0; ai < 2; ++ai) _Pragma("unroll") for (int m = 0; m < 4; ++m) _Pragma("unroll") for (int bj = 0; bj < 2; ++bj) { \
;         const int row = u.pm * 256 + ai * 128 + wr * 64 + m * 16 + fr, col = u.pn * 256 + bj * 128 + wc * 32 + 8 * fq; const f32x4 v0 = acc[ai][bj][m][0], v1 = acc[ai][bj][m][1]; (void)row; (void)col; __VA_ARGS__ }
;     __device__ __forceinline__ void operator()(const f32x4 (&acc)[2][2][4][2], const pg8::Unit& u, int wr, int wc, int fr, int fq, int par) const {
;         const LAS float* rp = red + par * 512 + wr * 64 + fr; const LAS float* cp = rp - (wr * 64 + fr) + 256 + wc * 32 + 8 * fq;
;         EPI_FOREACH( const f32x4 c0 = *(const LAS f32x4*)(cp + bj * 128), c1 = *(const LAS f32x4*)(cp + bj * 128 + 4); const float r = rp[ai * 128 + m * 16]; f32x4 a, b;
;             _Pragma("unroll") for (int q = 0; q < 4; ++q) { const float ra = fmaxf(v0[q] * r + c0[q], 0.f), rb = fmaxf(v1[q] * r + c1[q], 0.f); a[q] = ra * ra; b[q] = rb * rb; }
;             *(pg8::u32x4*)(O + (size_t)row * DFF + col) = pack8(a, b); )
;     }
	global_store_dwordx4 v229, v[218:221], s[98:99]
	v_pk_fma_f32 v[206:207], v[86:87], v[186:187], v[174:175] op_sel_hi:[1,0,1]
	v_pk_fma_f32 v[208:209], v[88:89], v[186:187], v[176:177] op_sel_hi:[1,0,1]
	v_pk_fma_f32 v[210:211], v[82:83], v[186:187], v[178:179] op_sel_hi:[1,0,1]
	v_pk_fma_f32 v[212:213], v[84:85], v[186:187], v[180:181] op_sel_hi:[1,0,1]
	v_max_f32_e32 v206, 0, v206
	v_max_f32_e32 v207, 0, v207
	v_max_f32_e32 v208, 0, v208
	v_max_f32_e32 v209, 0, v209
	v_max_f32_e32 v210, 0, v210
	v_max_f32_e32 v211, 0, v211
	v_max_f32_e32 v212, 0, v212
	v_max_f32_e32 v213, 0, v213
	v_pk_mul_f32 v[206:207], v[206:207], v[206:207]
	v_pk_mul_f32 v[208:209], v[208:209], v[208:209]
	v_pk_mul_f32 v[210:211], v[210:211], v[210:211]
	v_pk_mul_f32 v[212:213], v[212:213], v[212:213]
	v_cvt_pk_bf16_f32 v222, v206, v207
	v_cvt_pk_bf16_f32 v223, v208, v209
	v_cvt_pk_bf16_f32 v224, v210, v211
	v_cvt_pk_bf16_f32 v225, v212, v213
	global_store_dwordx4 v229, v[222:225], s[98:99] offset:256
	s_add_u32 s98, s98, 0x20000
	s_addc_u32 s99, s99, 0
	v_pk_fma_f32 v[198:199], v[110:111], v[188:189], v[166:167] op_sel_hi:[1,0,1]
	v_pk_fma_f32 v[200:201], v[112:113], v[188:189], v[168:169] op_sel_hi:[1,0,1]
	v_pk_fma_f32 v[202:203], v[106:107], v[188:189], v[170:171] op_sel_hi:[1,0,1]
	v_pk_fma_f32 v[204:205], v[108:109], v[188:189], v[172:173] op_sel_hi:[1,0,1]
	v_max_f32_e32 v198, 0, v198
	v_max_f32_e32 v199, 0, v199
	v_max_f32_e32 v200, 0, v200
	v_max_f32_e32 v201, 0, v201
	v_max_f32_e32 v202, 0, v202
	v_max_f32_e32 v203, 0, v203
	v_max_f32_e32 v204, 0, v204
	v_max_f32_e32 v205, 0, v205
	v_pk_mul_f32 v[198:199], v[198:199], v[198:199]
	v_pk_mul_f32 v[200:201], v[200:201], v[200:201]
	v_pk_mul_f32 v[202:203], v[202:203], v[202:203]
	v_pk_mul_f32 v[204:205], v[204:205], v[204:205]
	v_cvt_pk_bf16_f32 v214, v198, v199
	v_cvt_pk_bf16_f32 v215, v200, v201
	v_cvt_pk_bf16_f32 v216, v202, v203
	v_cvt_pk_bf16_f32 v217, v204, v205
	global_store_dwordx4 v229, v[214:217], s[98:99]
	v_pk_fma_f32 v[206:207], v[78:79], v[188:189], v[174:175] op_sel_hi:[1,0,1]
	v_pk_fma_f32 v[208:209], v[80:81], v[188:189], v[176:177] op_sel_hi:[1,0,1]
	v_pk_fma_f32 v[210:211], v[74:75], v[188:189], v[178:179] op_sel_hi:[1,0,1]
	v_pk_fma_f32 v[212:213], v[76:77], v[188:189], v[180:181] op_sel_hi:[1,0,1]
	v_max_f32_e32 v206, 0, v206
	v_max_f32_e32 v207, 0, v207
	v_max_f32_e32 v208, 0, v208
	v_max_f32_e32 v209, 0, v209
	v_max_f32_e32 v210, 0, v210
	v_max_f32_e32 v211, 0, v211
	v_max_f32_e32 v212, 0, v212
	v_max_f32_e32 v213, 0, v213
	v_pk_mul_f32 v[206:207], v[206:207], v[206:207]
	v_pk_mul_f32 v[208:209], v[208:209], v[208:209]
	v_pk_mul_f32 v[210:211], v[210:211], v[210:211]
	v_pk_mul_f32 v[212:213], v[212:213], v[212:213]
	v_cvt_pk_bf16_f32 v218, v206, v207
	v_cvt_pk_bf16_f32 v219, v208, v209
	v_cvt_pk_bf16_f32 v220, v210, v211
	v_cvt_pk_bf16_f32 v221, v212, v213
	global_store_dwordx4 v229, v[218:221], s[98:99] offset:256
	s_add_u32 s98, s98, 0xa0000
	s_addc_u32 s99, s99, 0
	v_pk_fma_f32 v[198:199], v[70:71], v[190:191], v[166:167] op_sel_hi:[1,0,1]
	v_pk_fma_f32 v[200:201], v[72:73], v[190:191], v[168:169] op_sel_hi:[1,0,1]
	v_pk_fma_f32 v[202:203], v[66:67], v[190:191], v[170:171] op_sel_hi:[1,0,1]
	v_pk_fma_f32 v[204:205], v[68:69], v[190:191], v[172:173] op_sel_hi:[1,0,1]
	v_max_f32_e32 v198, 0, v198
	v_max_f32_e32 v199, 0, v199
	v_max_f32_e32 v200, 0, v200
	v_max_f32_e32 v201, 0, v201
	v_max_f32_e32 v202, 0, v202
	v_max_f32_e32 v203, 0, v203
	v_max_f32_e32 v204, 0, v204
	v_max_f32_e32 v205, 0, v205
	v_pk_mul_f32 v[198:199], v[198:199], v[198:199]
	v_pk_mul_f32 v[200:201], v[200:201], v[200:201]
	v_pk_mul_f32 v[202:203], v[202:203], v[202:203]
	v_pk_mul_f32 v[204:205], v[204:205], v[204:205]
	v_cvt_pk_bf16_f32 v222, v198, v199
	v_cvt_pk_bf16_f32 v223, v200, v201
	v_cvt_pk_bf16_f32 v224, v202, v203
	v_cvt_pk_bf16_f32 v225, v204, v205
	global_store_dwordx4 v229, v[222:225], s[98:99]
	v_pk_fma_f32 v[206:207], v[38:39], v[190:191], v[174:175] op_sel_hi:[1,0,1]
	v_pk_fma_f32 v[208:209], v[40:41], v[190:191], v[176:177] op_sel_hi:[1,0,1]
	v_pk_fma_f32 v[210:211], v[34:35], v[190:191], v[178:179] op_sel_hi:[1,0,1]
	v_pk_fma_f32 v[212:213], v[36:37], v[190:191], v[180:181] op_sel_hi:[1,0,1]
	v_max_f32_e32 v206, 0, v206
	v_max_f32_e32 v207, 0, v207
	v_max_f32_e32 v208, 0, v208
	v_max_f32_e32 v209, 0, v209
	v_max_f32_e32 v210, 0, v210
	v_max_f32_e32 v211, 0, v211
	v_max_f32_e32 v212, 0, v212
	v_max_f32_e32 v213, 0, v213
	v_pk_mul_f32 v[206:207], v[206:207], v[206:207]
	v_pk_mul_f32 v[208:209], v[208:209], v[208:209]
	v_pk_mul_f32 v[210:211], v[210:211], v[210:211]
	v_pk_mul_f32 v[212:213], v[212:213], v[212:213]
	v_cvt_pk_bf16_f32 v214, v206, v207
	v_cvt_pk_bf16_f32 v215, v208, v209
	v_cvt_pk_bf16_f32 v216, v210, v211
	v_cvt_pk_bf16_f32 v217, v212, v213
	global_store_dwordx4 v229, v[214:217], s[98:99] offset:256
	s_add_u32 s98, s98, 0x20000
	s_addc_u32 s99, s99, 0
	v_pk_fma_f32 v[198:199], v[62:63], v[192:193], v[166:167] op_sel_hi:[1,0,1]
	v_pk_fma_f32 v[200:201], v[64:65], v[192:193], v[168:169] op_sel_hi:[1,0,1]
	v_pk_fma_f32 v[202:203], v[58:59], v[192:193], v[170:171] op_sel_hi:[1,0,1]
	v_pk_fma_f32 v[204:205], v[60:61], v[192:193], v[172:173] op_sel_hi:[1,0,1]
	v_max_f32_e32 v198, 0, v198
	v_max_f32_e32 v199, 0, v199
	v_max_f32_e32 v200, 0, v200
	v_max_f32_e32 v201, 0, v201
	v_max_f32_e32 v202, 0, v202
	v_max_f32_e32 v203, 0, v203
	v_max_f32_e32 v204, 0, v204
	v_max_f32_e32 v205, 0, v205
	v_pk_mul_f32 v[198:199], v[198:199], v[198:199]
	v_pk_mul_f32 v[200:201], v[200:201], v[200:201]
; #define LAS __attribute__((address_space(3)))
; __device__ __forceinline__ pg8::u32x4 pack8(const f32x4 a, const f32x4 b) { pg8::u32x4 w; w.x = pg8::cvt_pk_bf16(a[0], a[1]); w.y = pg8::cvt_pk_bf16(a[2], a[3]); w.z = pg8::cvt_pk_bf16(b[0], b[1]); w.w = pg8::cvt_pk_bf16(b[2], b[3]); return w; }
; #define EPI_FOREACH(...) _Pragma("unroll") for (int ai = 0; ai < 2; ++ai) _Pragma("unroll") for (int m = 0; m < 4; ++m) _Pragma("unroll") for (int bj = 0; bj < 2; ++bj) { \
;         const int row = u.pm * 256 + ai * 128 + wr * 64 + m * 16 + fr, col = u.pn * 256 + bj * 128 + wc * 32 + 8 * fq; const f32x4 v0 = acc[ai][bj][m][0], v1 = acc[ai][bj][m][1]; (void)row; (void)col; __VA_ARGS__ }
;     __device__ __forceinline__ void pre_issue(const pg8::Unit& u, int tid, f32x4& v) const {
;         if (tid < 256) v = *(const f32x4*)(ss + ((size_t)u.pm * 256 + tid) * 4);
;         else v[0] = cf[(size_t)(u.pm < 64 ? (u.pm >> 3) : 8) * DFF + u.pn * 256 + (tid - 256)]; }
;     __device__ __forceinline__ void pre_commit(int tid, int par, const f32x4& v) const {
;         red[par * 512 + tid] = tid < 256 ? rsqrtf((v[0] + v[1] + v[2] + v[3]) * (1.f / DM) + EPS) : v[0]; }
;     __device__ __forceinline__ void operator()(const f32x4 (&acc)[2][2][4][2], const pg8::Unit& u, int wr, int wc, int fr, int fq, int par) const {
;         const LAS float* rp = red + par * 512 + wr * 64 + fr; const LAS float* cp = rp - (wr * 64 + fr) + 256 + wc * 32 + 8 * fq;
;         EPI_FOREACH( const f32x4 c0 = *(const LAS f32x4*)(cp + bj * 128), c1 = *(const LAS f32x4*)(cp + bj * 128 + 4); const float r = rp[ai * 128 + m * 16]; f32x4 a, b;
;             _Pragma("unroll") for (int q = 0; q < 4; ++q) { const float ra = fmaxf(v0[q] * r + c0[q], 0.f), rb = fmaxf(v1[q] * r + c1[q], 0.f); a[q] = ra * ra; b[q] = rb * rb; }
;             *(pg8::u32x4*)(O + (size_t)row * DFF + col) = pack8(a, b); )
;     }
	v_pk_mul_f32 v[202:203], v[202:203], v[202:203]
	v_pk_mul_f32 v[204:205], v[204:205], v[204:205]
	v_cvt_pk_bf16_f32 v218, v198, v199
	v_cvt_pk_bf16_f32 v219, v200, v201
	v_cvt_pk_bf16_f32 v220, v202, v203
	v_cvt_pk_bf16_f32 v221, v204, v205
	global_store_dwordx4 v229, v[218:221], s[98:99]
	v_pk_fma_f32 v[206:207], v[30:31], v[192:193], v[174:175] op_sel_hi:[1,0,1]
	v_pk_fma_f32 v[208:209], v[32:33], v[192:193], v[176:177] op_sel_hi:[1,0,1]
	v_pk_fma_f32 v[210:211], v[26:27], v[192:193], v[178:179] op_sel_hi:[1,0,1]
	v_pk_fma_f32 v[212:213], v[28:29], v[192:193], v[180:181] op_sel_hi:[1,0,1]
	v_max_f32_e32 v206, 0, v206
	v_max_f32_e32 v207, 0, v207
	v_max_f32_e32 v208, 0, v208
	v_max_f32_e32 v209, 0, v209
	v_max_f32_e32 v210, 0, v210
	v_max_f32_e32 v211, 0, v211
	v_max_f32_e32 v212, 0, v212
	v_max_f32_e32 v213, 0, v213
	v_pk_mul_f32 v[206:207], v[206:207], v[206:207]
	v_pk_mul_f32 v[208:209], v[208:209], v[208:209]
	v_pk_mul_f32 v[210:211], v[210:211], v[210:211]
	v_pk_mul_f32 v[212:213], v[212:213], v[212:213]
	v_cvt_pk_bf16_f32 v222, v206, v207
	v_cvt_pk_bf16_f32 v223, v208, v209
	v_cvt_pk_bf16_f32 v224, v210, v211
	v_cvt_pk_bf16_f32 v225, v212, v213
	global_store_dwordx4 v229, v[222:225], s[98:99] offset:256
	s_add_u32 s98, s98, 0x20000
	s_addc_u32 s99, s99, 0
	v_pk_fma_f32 v[198:199], v[54:55], v[194:195], v[166:167] op_sel_hi:[1,0,1]
	v_pk_fma_f32 v[200:201], v[56:57], v[194:195], v[168:169] op_sel_hi:[1,0,1]
	v_pk_fma_f32 v[202:203], v[50:51], v[194:195], v[170:171] op_sel_hi:[1,0,1]
	v_pk_fma_f32 v[204:205], v[52:53], v[194:195], v[172:173] op_sel_hi:[1,0,1]
	v_max_f32_e32 v198, 0, v198
	v_max_f32_e32 v199, 0, v199
	v_max_f32_e32 v200, 0, v200
	v_max_f32_e32 v201, 0, v201
	v_max_f32_e32 v202, 0, v202
	v_max_f32_e32 v203, 0, v203
	v_max_f32_e32 v204, 0, v204
	v_max_f32_e32 v205, 0, v205
	v_pk_mul_f32 v[198:199], v[198:199], v[198:199]
	v_pk_mul_f32 v[200:201], v[200:201], v[200:201]
	v_pk_mul_f32 v[202:203], v[202:203], v[202:203]
	v_pk_mul_f32 v[204:205], v[204:205], v[204:205]
	v_cvt_pk_bf16_f32 v214, v198, v199
	v_cvt_pk_bf16_f32 v215, v200, v201
	v_cvt_pk_bf16_f32 v216, v202, v203
	v_cvt_pk_bf16_f32 v217, v204, v205
	global_store_dwordx4 v229, v[214:217], s[98:99]
	v_pk_fma_f32 v[206:207], v[22:23], v[194:195], v[174:175] op_sel_hi:[1,0,1]
	v_pk_fma_f32 v[208:209], v[24:25], v[194:195], v[176:177] op_sel_hi:[1,0,1]
	v_pk_fma_f32 v[210:211], v[18:19], v[194:195], v[178:179] op_sel_hi:[1,0,1]
	v_pk_fma_f32 v[212:213], v[20:21], v[194:195], v[180:181] op_sel_hi:[1,0,1]
	v_max_f32_e32 v206, 0, v206
	v_max_f32_e32 v207, 0, v207
	v_max_f32_e32 v208, 0, v208
	v_max_f32_e32 v209, 0, v209
	v_max_f32_e32 v210, 0, v210
	v_max_f32_e32 v211, 0, v211
	v_max_f32_e32 v212, 0, v212
	v_max_f32_e32 v213, 0, v213
	v_pk_mul_f32 v[206:207], v[206:207], v[206:207]
	v_pk_mul_f32 v[208:209], v[208:209], v[208:209]
	v_pk_mul_f32 v[210:211], v[210:211], v[210:211]
	v_pk_mul_f32 v[212:213], v[212:213], v[212:213]
	v_cvt_pk_bf16_f32 v218, v206, v207
	v_cvt_pk_bf16_f32 v219, v208, v209
	v_cvt_pk_bf16_f32 v220, v210, v211
	v_cvt_pk_bf16_f32 v221, v212, v213
	global_store_dwordx4 v229, v[218:221], s[98:99] offset:256
	s_add_u32 s98, s98, 0x20000
	s_addc_u32 s99, s99, 0
	v_pk_fma_f32 v[198:199], v[46:47], v[196:197], v[166:167] op_sel_hi:[1,0,1]
	v_pk_fma_f32 v[200:201], v[48:49], v[196:197], v[168:169] op_sel_hi:[1,0,1]
	v_pk_fma_f32 v[202:203], v[42:43], v[196:197], v[170:171] op_sel_hi:[1,0,1]
	v_pk_fma_f32 v[204:205], v[44:45], v[196:197], v[172:173] op_sel_hi:[1,0,1]
	v_max_f32_e32 v198, 0, v198
	v_max_f32_e32 v199, 0, v199
	v_max_f32_e32 v200, 0, v200
	v_max_f32_e32 v201, 0, v201
	v_max_f32_e32 v202, 0, v202
	v_max_f32_e32 v203, 0, v203
	v_max_f32_e32 v204, 0, v204
	v_max_f32_e32 v205, 0, v205
	v_pk_mul_f32 v[198:199], v[198:199], v[198:199]
	v_pk_mul_f32 v[200:201], v[200:201], v[200:201]
	v_pk_mul_f32 v[202:203], v[202:203], v[202:203]
	v_pk_mul_f32 v[204:205], v[204:205], v[204:205]
	v_cvt_pk_bf16_f32 v222, v198, v199
	v_cvt_pk_bf16_f32 v223, v200, v201
	v_cvt_pk_bf16_f32 v224, v202, v203
	v_cvt_pk_bf16_f32 v225, v204, v205
	global_store_dwordx4 v229, v[222:225], s[98:99]
	v_pk_fma_f32 v[206:207], v[14:15], v[196:197], v[174:175] op_sel_hi:[1,0,1]
	v_pk_fma_f32 v[208:209], v[16:17], v[196:197], v[176:177] op_sel_hi:[1,0,1]
	v_pk_fma_f32 v[210:211], v[10:11], v[196:197], v[178:179] op_sel_hi:[1,0,1]
	v_pk_fma_f32 v[212:213], v[12:13], v[196:197], v[180:181] op_sel_hi:[1,0,1]
	v_max_f32_e32 v206, 0, v206
	v_max_f32_e32 v207, 0, v207
	v_max_f32_e32 v208, 0, v208
	v_max_f32_e32 v209, 0, v209
	v_max_f32_e32 v210, 0, v210
	v_max_f32_e32 v211, 0, v211
	v_max_f32_e32 v212, 0, v212
	v_max_f32_e32 v213, 0, v213
	v_pk_mul_f32 v[206:207], v[206:207], v[206:207]
	v_pk_mul_f32 v[208:209], v[208:209], v[208:209]
	v_pk_mul_f32 v[210:211], v[210:211], v[210:211]
	v_pk_mul_f32 v[212:213], v[212:213], v[212:213]
	v_cvt_pk_bf16_f32 v214, v206, v207
	v_cvt_pk_bf16_f32 v215, v208, v209
	v_cvt_pk_bf16_f32 v216, v210, v211
	v_cvt_pk_bf16_f32 v217, v212, v213
	global_store_dwordx4 v229, v[214:217], s[98:99] offset:256
	s_and_b64 vcc, exec, s[10:11]
	s_cbranch_vccnz .LBB0_1724
	s_waitcnt vmcnt(0)
	v_mov_b32_e32 v6, v2
	s_and_saveexec_b64 s[10:11], s[6:7]
	s_cbranch_execz .LBB0_1715
	v_add_f32_e32 v6, v2, v3
	v_add_f32_e32 v6, v4, v6
	v_add_f32_e32 v6, v5, v6
	v_fmamk_f32 v6, v6, 0x3a800000, v164
	v_mul_f32_e32 v7, 0x4b800000, v6
	v_cmp_gt_f32_e32 vcc, s77, v6
	s_nop 1
	v_cndmask_b32_e32 v6, v6, v7, vcc
	v_rsq_f32_e32 v6, v6
	s_nop 0
	v_mul_f32_e32 v7, 0x45800000, v6
	v_cndmask_b32_e32 v6, v6, v7, vcc

; #define LAS __attribute__((address_space(3)))
; __device__ __forceinline__ pg8::u32x4 pack8(const f32x4 a, const f32x4 b) { pg8::u32x4 w; w.x = pg8::cvt_pk_bf16(a[0], a[1]); w.y = pg8::cvt_pk_bf16(a[2], a[3]); w.z = pg8::cvt_pk_bf16(b[0], b[1]); w.w = pg8::cvt_pk_bf16(b[2], b[3]); return w; }
; #define EPI_FOREACH(...) _Pragma("unroll") for (int ai = 0; ai < 2; ++ai) _Pragma("unroll") for (int m = 0; m < 4; ++m) _Pragma("unroll") for (int bj = 0; bj < 2; ++bj) { \
;         const int row = u.pm * 256 + ai * 128 + wr * 64 + m * 16 + fr, col = u.pn * 256 + bj * 128 + wc * 32 + 8 * fq; const f32x4 v0 = acc[ai][bj][m][0], v1 = acc[ai][bj][m][1]; (void)row; (void)col; __VA_ARGS__ }
;     __device__ __forceinline__ void operator()(const f32x4 (&acc)[2][2][4][2], const pg8::Unit& u, int wr, int wc, int fr, int fq, int par) const {
;         const LAS float* rp = red + par * 512 + wr * 64 + fr; const LAS float* cp = rp - (wr * 64 + fr) + 256 + wc * 32 + 8 * fq;
;         EPI_FOREACH( const f32x4 c0 = *(const LAS f32x4*)(cp + bj * 128), c1 = *(const LAS f32x4*)(cp + bj * 128 + 4); const float r = rp[ai * 128 + m * 16]; f32x4 a, b;
;             _Pragma("unroll") for (int q = 0; q < 4; ++q) { const float ra = fmaxf(v0[q] * r + c0[q], 0.f), rb = fmaxf(v1[q] * r + c1[q], 0.f); a[q] = ra * ra; b[q] = rb * rb; }
;             *(pg8::u32x4*)(O + (size_t)row * DFF + col) = pack8(a, b); )
;     }
.LBB0_3338:
	s_add_u32 s36, s27, 0xffffff00
	s_addc_u32 s37, s68, -1
	s_lshl_b32 s10, s66, 11
	s_and_b32 s10, s10, 0x800
	v_add_u32_e32 v226, s10, v162
	v_lshl_add_u32 v227, v161, 2, v226
	s_lshl_b32 s10, s59, 2
	v_lshlrev_b32_e32 v228, 2, v159
	v_add3_u32 v227, v227, s10, v228
	ds_read_b128 v[166:169], v227 offset:1024
	ds_read_b128 v[170:173], v227 offset:1040
	ds_read_b128 v[174:177], v227 offset:1536
	ds_read_b128 v[178:181], v227 offset:1552
	ds_read_b32 v182, v226
	ds_read_b32 v184, v226 offset:64
	ds_read_b32 v186, v226 offset:128
	ds_read_b32 v188, v226 offset:192
	ds_read_b32 v190, v226 offset:512
	ds_read_b32 v192, v226 offset:576
	ds_read_b32 v194, v226 offset:640
	ds_read_b32 v196, v226 offset:704
	v_lshl_add_u32 v229, s14, 8, v158
	v_lshlrev_b32_e32 v229, 13, v229
	v_lshl_or_b32 v228, s54, 8, v163
	v_lshl_add_u32 v229, v228, 1, v229
	s_mov_b64 s[98:99], s[20:21]
	s_waitcnt lgkmcnt(0)
	v_pk_fma_f32 v[198:199], v[6:7], v[182:183], v[166:167] op_sel_hi:[1,0,1]
	v_pk_fma_f32 v[200:201], v[8:9], v[182:183], v[168:169] op_sel_hi:[1,0,1]
	v_pk_fma_f32 v[202:203], v[130:131], v[182:183], v[170:171] op_sel_hi:[1,0,1]
	v_pk_fma_f32 v[204:205], v[132:133], v[182:183], v[172:173] op_sel_hi:[1,0,1]
	v_max_f32_e32 v198, 0, v198
	v_max_f32_e32 v199, 0, v199
	v_max_f32_e32 v200, 0, v200
	v_max_f32_e32 v201, 0, v201
	v_max_f32_e32 v202, 0, v202
	v_max_f32_e32 v203, 0, v203
	v_max_f32_e32 v204, 0, v204
	v_max_f32_e32 v205, 0, v205
	v_pk_mul_f32 v[198:199], v[198:199], v[198:199]
	v_pk_mul_f32 v[200:201], v[200:201], v[200:201]
	v_pk_mul_f32 v[202:203], v[202:203], v[202:203]
	v_pk_mul_f32 v[204:205], v[204:205], v[204:205]
	v_cvt_pk_bf16_f32 v214, v198, v199
	v_cvt_pk_bf16_f32 v215, v200, v201
	v_cvt_pk_bf16_f32 v216, v202, v203
	v_cvt_pk_bf16_f32 v217, v204, v205
	global_store_dwordx4 v229, v[214:217], s[98:99]
	v_pk_fma_f32 v[206:207], v[102:103], v[182:183], v[174:175] op_sel_hi:[1,0,1]
	v_pk_fma_f32 v[208:209], v[104:105], v[182:183], v[176:177] op_sel_hi:[1,0,1]
	v_pk_fma_f32 v[210:211], v[98:99], v[182:183], v[178:179] op_sel_hi:[1,0,1]
	v_pk_fma_f32 v[212:213], v[100:101], v[182:183], v[180:181] op_sel_hi:[1,0,1]
	v_max_f32_e32 v206, 0, v206
	v_max_f32_e32 v207, 0, v207
	v_max_f32_e32 v208, 0, v208
	v_max_f32_e32 v209, 0, v209
	v_max_f32_e32 v210, 0, v210
	v_max_f32_e32 v211, 0, v211
	v_max_f32_e32 v212, 0, v212
	v_max_f32_e32 v213, 0, v213
	v_pk_mul_f32 v[206:207], v[206:207], v[206:207]
	v_pk_mul_f32 v[208:209], v[208:209], v[208:209]
	v_pk_mul_f32 v[210:211], v[210:211], v[210:211]
	v_pk_mul_f32 v[212:213], v[212:213], v[212:213]
	v_cvt_pk_bf16_f32 v218, v206, v207
	v_cvt_pk_bf16_f32 v219, v208, v209
	v_cvt_pk_bf16_f32 v220, v210, v211
	v_cvt_pk_bf16_f32 v221, v212, v213
	global_store_dwordx4 v229, v[218:221], s[98:99] offset:256
	s_add_u32 s98, s98, 0x20000
	s_addc_u32 s99, s99, 0
	v_pk_fma_f32 v[198:199], v[126:127], v[184:185], v[166:167] op_sel_hi:[1,0,1]
	v_pk_fma_f32 v[200:201], v[128:129], v[184:185], v[168:169] op_sel_hi:[1,0,1]
	v_pk_fma_f32 v[202:203], v[122:123], v[184:185], v[170:171] op_sel_hi:[1,0,1]
	v_pk_fma_f32 v[204:205], v[124:125], v[184:185], v[172:173] op_sel_hi:[1,0,1]
	v_max_f32_e32 v198, 0, v198
	v_max_f32_e32 v199, 0, v199
	v_max_f32_e32 v200, 0, v200
	v_max_f32_e32 v201, 0, v201
	v_max_f32_e32 v202, 0, v202
	v_max_f32_e32 v203, 0, v203
	v_max_f32_e32 v204, 0, v204
	v_max_f32_e32 v205, 0, v205
	v_pk_mul_f32 v[198:199], v[198:199], v[198:199]
	v_pk_mul_f32 v[200:201], v[200:201], v[200:201]
	v_pk_mul_f32 v[202:203], v[202:203], v[202:203]
	v_pk_mul_f32 v[204:205], v[204:205], v[204:205]
	v_cvt_pk_bf16_f32 v222, v198, v199
	v_cvt_pk_bf16_f32 v223, v200, v201
	v_cvt_pk_bf16_f32 v224, v202, v203
	v_cvt_pk_bf16_f32 v225, v204, v205
	global_store_dwordx4 v229, v[222:225], s[98:99]
	v_pk_fma_f32 v[206:207], v[94:95], v[184:185], v[174:175] op_sel_hi:[1,0,1]
	v_pk_fma_f32 v[208:209], v[96:97], v[184:185], v[176:177] op_sel_hi:[1,0,1]
	v_pk_fma_f32 v[210:211], v[90:91], v[184:185], v[178:179] op_sel_hi:[1,0,1]
	v_pk_fma_f32 v[212:213], v[92:93], v[184:185], v[180:181] op_sel_hi:[1,0,1]
	v_max_f32_e32 v206, 0, v206
	v_max_f32_e32 v207, 0, v207
	v_max_f32_e32 v208, 0, v208
	v_max_f32_e32 v209, 0, v209
	v_max_f32_e32 v210, 0, v210
	v_max_f32_e32 v211, 0, v211
	v_max_f32_e32 v212, 0, v212
	v_max_f32_e32 v213, 0, v213
	v_pk_mul_f32 v[206:207], v[206:207], v[206:207]
	v_pk_mul_f32 v[208:209], v[208:209], v[208:209]
	v_pk_mul_f32 v[210:211], v[210:211], v[210:211]
	v_pk_mul_f32 v[212:213], v[212:213], v[212:213]
	v_cvt_pk_bf16_f32 v214, v206, v207
	v_cvt_pk_bf16_f32 v215, v208, v209
	v_cvt_pk_bf16_f32 v216, v210, v211
	v_cvt_pk_bf16_f32 v217, v212, v213
	global_store_dwordx4 v229, v[214:217], s[98:99] offset:256
	s_add_u32 s98, s98, 0x20000
	s_addc_u32 s99, s99, 0
	v_pk_fma_f32 v[198:199], v[118:119], v[186:187], v[166:167] op_sel_hi:[1,0,1]
	v_pk_fma_f32 v[200:201], v[120:121], v[186:187], v[168:169] op_sel_hi:[1,0,1]
	v_pk_fma_f32 v[202:203], v[114:115], v[186:187], v[170:171] op_sel_hi:[1,0,1]
	v_pk_fma_f32 v[204:205], v[116:117], v[186:187], v[172:173] op_sel_hi:[1,0,1]
	v_max_f32_e32 v198, 0, v198
	v_max_f32_e32 v199, 0, v199
	v_max_f32_e32 v200, 0, v200
	v_max_f32_e32 v201, 0, v201
	v_max_f32_e32 v202, 0, v202
	v_max_f32_e32 v203, 0, v203
	v_max_f32_e32 v204, 0, v204
	v_max_f32_e32 v205, 0, v205
	v_pk_mul_f32 v[198:199], v[198:199], v[198:199]
	v_pk_mul_f32 v[200:201], v[200:201], v[200:201]
	v_pk_mul_f32 v[202:203], v[202:203], v[202:203]
	v_pk_mul_f32 v[204:205], v[204:205], v[204:205]
	v_cvt_pk_bf16_f32 v218, v198, v199
	v_cvt_pk_bf16_f32 v219, v200, v201
	v_cvt_pk_bf16_f32 v220, v202, v203
	v_cvt_pk_bf16_f32 v221, v204, v205
; #define LAS __attribute__((address_space(3)))
; __device__ __forceinline__ pg8::u32x4 pack8(const f32x4 a, const f32x4 b) { pg8::u32x4 w; w.x = pg8::cvt_pk_bf16(a[0], a[1]); w.y = pg8::cvt_pk_bf16(a[2], a[3]); w.z = pg8::cvt_pk_bf16(b[0], b[1]); w.w = pg8::cvt_pk_bf16(b[2], b[3]); return w; }
; #define EPI_FOREACH(...) _Pragma("unroll") for (int ai = 0; ai < 2; ++ai) _Pragma("unroll") for (int m = 0; m < 4; ++m) _Pragma("unroll") for (int bj = 0; bj < 2; ++bj) { \
;         const int row = u.pm * 256 + ai * 128 + wr * 64 + m * 16 + fr, col = u.pn * 256 + bj * 128 + wc * 32 + 8 * fq; const f32x4 v0 = acc[ai][bj][m][0], v1 = acc[ai][bj][m][1]; (void)row; (void)col; __VA_ARGS__ }
;     __device__ __forceinline__ void operator()(const f32x4 (&acc)[2][2][4][2], const pg8::Unit& u, int wr, int wc, int fr, int fq, int par) const {
;         const LAS float* rp = red + par * 512 + wr * 64 + fr; const LAS float* cp = rp - (wr * 64 + fr) + 256 + wc * 32 + 8 * fq;
;         EPI_FOREACH( const f32x4 c0 = *(const LAS f32x4*)(cp + bj * 128), c1 = *(const LAS f32x4*)(cp + bj * 128 + 4); const float r = rp[ai * 128 + m * 16]; f32x4 a, b;
;             _Pragma("unroll") for (int q = 0; q < 4; ++q) { const float ra = fmaxf(v0[q] * r + c0[q], 0.f), rb = fmaxf(v1[q] * r + c1[q], 0.f); a[q] = ra * ra; b[q] = rb * rb; }
;             *(pg8::u32x4*)(O + (size_t)row * DFF + col) = pack8(a, b); )
;     }
	global_store_dwordx4 v229, v[218:221], s[98:99]
	v_pk_fma_f32 v[206:207], v[86:87], v[186:187], v[174:175] op_sel_hi:[1,0,1]
	v_pk_fma_f32 v[208:209], v[88:89], v[186:187], v[176:177] op_sel_hi:[1,0,1]
	v_pk_fma_f32 v[210:211], v[82:83], v[186:187], v[178:179] op_sel_hi:[1,0,1]
	v_pk_fma_f32 v[212:213], v[84:85], v[186:187], v[180:181] op_sel_hi:[1,0,1]
	v_max_f32_e32 v206, 0, v206
	v_max_f32_e32 v207, 0, v207
	v_max_f32_e32 v208, 0, v208
	v_max_f32_e32 v209, 0, v209
	v_max_f32_e32 v210, 0, v210
	v_max_f32_e32 v211, 0, v211
	v_max_f32_e32 v212, 0, v212
	v_max_f32_e32 v213, 0, v213
	v_pk_mul_f32 v[206:207], v[206:207], v[206:207]
	v_pk_mul_f32 v[208:209], v[208:209], v[208:209]
	v_pk_mul_f32 v[210:211], v[210:211], v[210:211]
	v_pk_mul_f32 v[212:213], v[212:213], v[212:213]
	v_cvt_pk_bf16_f32 v222, v206, v207
	v_cvt_pk_bf16_f32 v223, v208, v209
	v_cvt_pk_bf16_f32 v224, v210, v211
	v_cvt_pk_bf16_f32 v225, v212, v213
	global_store_dwordx4 v229, v[222:225], s[98:99] offset:256
	s_add_u32 s98, s98, 0x20000
	s_addc_u32 s99, s99, 0
	v_pk_fma_f32 v[198:199], v[110:111], v[188:189], v[166:167] op_sel_hi:[1,0,1]
	v_pk_fma_f32 v[200:201], v[112:113], v[188:189], v[168:169] op_sel_hi:[1,0,1]
	v_pk_fma_f32 v[202:203], v[106:107], v[188:189], v[170:171] op_sel_hi:[1,0,1]
	v_pk_fma_f32 v[204:205], v[108:109], v[188:189], v[172:173] op_sel_hi:[1,0,1]
	v_max_f32_e32 v198, 0, v198
	v_max_f32_e32 v199, 0, v199
	v_max_f32_e32 v200, 0, v200
	v_max_f32_e32 v201, 0, v201
	v_max_f32_e32 v202, 0, v202
	v_max_f32_e32 v203, 0, v203
	v_max_f32_e32 v204, 0, v204
	v_max_f32_e32 v205, 0, v205
	v_pk_mul_f32 v[198:199], v[198:199], v[198:199]
	v_pk_mul_f32 v[200:201], v[200:201], v[200:201]
	v_pk_mul_f32 v[202:203], v[202:203], v[202:203]
	v_pk_mul_f32 v[204:205], v[204:205], v[204:205]
	v_cvt_pk_bf16_f32 v214, v198, v199
	v_cvt_pk_bf16_f32 v215, v200, v201
	v_cvt_pk_bf16_f32 v216, v202, v203
	v_cvt_pk_bf16_f32 v217, v204, v205
	global_store_dwordx4 v229, v[214:217], s[98:99]
	v_pk_fma_f32 v[206:207], v[78:79], v[188:189], v[174:175] op_sel_hi:[1,0,1]
	v_pk_fma_f32 v[208:209], v[80:81], v[188:189], v[176:177] op_sel_hi:[1,0,1]
	v_pk_fma_f32 v[210:211], v[74:75], v[188:189], v[178:179] op_sel_hi:[1,0,1]
	v_pk_fma_f32 v[212:213], v[76:77], v[188:189], v[180:181] op_sel_hi:[1,0,1]
	v_max_f32_e32 v206, 0, v206
	v_max_f32_e32 v207, 0, v207
	v_max_f32_e32 v208, 0, v208
	v_max_f32_e32 v209, 0, v209
	v_max_f32_e32 v210, 0, v210
	v_max_f32_e32 v211, 0, v211
	v_max_f32_e32 v212, 0, v212
	v_max_f32_e32 v213, 0, v213
	v_pk_mul_f32 v[206:207], v[206:207], v[206:207]
	v_pk_mul_f32 v[208:209], v[208:209], v[208:209]
	v_pk_mul_f32 v[210:211], v[210:211], v[210:211]
	v_pk_mul_f32 v[212:213], v[212:213], v[212:213]
	v_cvt_pk_bf16_f32 v218, v206, v207
	v_cvt_pk_bf16_f32 v219, v208, v209
	v_cvt_pk_bf16_f32 v220, v210, v211
	v_cvt_pk_bf16_f32 v221, v212, v213
	global_store_dwordx4 v229, v[218:221], s[98:99] offset:256
	s_add_u32 s98, s98, 0xa0000
	s_addc_u32 s99, s99, 0
	v_pk_fma_f32 v[198:199], v[70:71], v[190:191], v[166:167] op_sel_hi:[1,0,1]
	v_pk_fma_f32 v[200:201], v[72:73], v[190:191], v[168:169] op_sel_hi:[1,0,1]
	v_pk_fma_f32 v[202:203], v[66:67], v[190:191], v[170:171] op_sel_hi:[1,0,1]
	v_pk_fma_f32 v[204:205], v[68:69], v[190:191], v[172:173] op_sel_hi:[1,0,1]
	v_max_f32_e32 v198, 0, v198
	v_max_f32_e32 v199, 0, v199
	v_max_f32_e32 v200, 0, v200
	v_max_f32_e32 v201, 0, v201
	v_max_f32_e32 v202, 0, v202
	v_max_f32_e32 v203, 0, v203
	v_max_f32_e32 v204, 0, v204
	v_max_f32_e32 v205, 0, v205
	v_pk_mul_f32 v[198:199], v[198:199], v[198:199]
	v_pk_mul_f32 v[200:201], v[200:201], v[200:201]
	v_pk_mul_f32 v[202:203], v[202:203], v[202:203]
	v_pk_mul_f32 v[204:205], v[204:205], v[204:205]
	v_cvt_pk_bf16_f32 v222, v198, v199
	v_cvt_pk_bf16_f32 v223, v200, v201
	v_cvt_pk_bf16_f32 v224, v202, v203
	v_cvt_pk_bf16_f32 v225, v204, v205
	global_store_dwordx4 v229, v[222:225], s[98:99]
	v_pk_fma_f32 v[206:207], v[38:39], v[190:191], v[174:175] op_sel_hi:[1,0,1]
	v_pk_fma_f32 v[208:209], v[40:41], v[190:191], v[176:177] op_sel_hi:[1,0,1]
	v_pk_fma_f32 v[210:211], v[34:35], v[190:191], v[178:179] op_sel_hi:[1,0,1]
	v_pk_fma_f32 v[212:213], v[36:37], v[190:191], v[180:181] op_sel_hi:[1,0,1]
	v_max_f32_e32 v206, 0, v206
	v_max_f32_e32 v207, 0, v207
	v_max_f32_e32 v208, 0, v208
	v_max_f32_e32 v209, 0, v209
	v_max_f32_e32 v210, 0, v210
	v_max_f32_e32 v211, 0, v211
	v_max_f32_e32 v212, 0, v212
	v_max_f32_e32 v213, 0, v213
	v_pk_mul_f32 v[206:207], v[206:207], v[206:207]
	v_pk_mul_f32 v[208:209], v[208:209], v[208:209]
	v_pk_mul_f32 v[210:211], v[210:211], v[210:211]
	v_pk_mul_f32 v[212:213], v[212:213], v[212:213]
	v_cvt_pk_bf16_f32 v214, v206, v207
	v_cvt_pk_bf16_f32 v215, v208, v209
	v_cvt_pk_bf16_f32 v216, v210, v211
	v_cvt_pk_bf16_f32 v217, v212, v213
	global_store_dwordx4 v229, v[214:217], s[98:99] offset:256
	s_add_u32 s98, s98, 0x20000
	s_addc_u32 s99, s99, 0
	v_pk_fma_f32 v[198:199], v[62:63], v[192:193], v[166:167] op_sel_hi:[1,0,1]
	v_pk_fma_f32 v[200:201], v[64:65], v[192:193], v[168:169] op_sel_hi:[1,0,1]
	v_pk_fma_f32 v[202:203], v[58:59], v[192:193], v[170:171] op_sel_hi:[1,0,1]
	v_pk_fma_f32 v[204:205], v[60:61], v[192:193], v[172:173] op_sel_hi:[1,0,1]
	v_max_f32_e32 v198, 0, v198
	v_max_f32_e32 v199, 0, v199
	v_max_f32_e32 v200, 0, v200
	v_max_f32_e32 v201, 0, v201
	v_max_f32_e32 v202, 0, v202
	v_max_f32_e32 v203, 0, v203
	v_max_f32_e32 v204, 0, v204
	v_max_f32_e32 v205, 0, v205
	v_pk_mul_f32 v[198:199], v[198:199], v[198:199]
	v_pk_mul_f32 v[200:201], v[200:201], v[200:201]
; #define LAS __attribute__((address_space(3)))
; __device__ __forceinline__ pg8::u32x4 pack8(const f32x4 a, const f32x4 b) { pg8::u32x4 w; w.x = pg8::cvt_pk_bf16(a[0], a[1]); w.y = pg8::cvt_pk_bf16(a[2], a[3]); w.z = pg8::cvt_pk_bf16(b[0], b[1]); w.w = pg8::cvt_pk_bf16(b[2], b[3]); return w; }
; #define EPI_FOREACH(...) _Pragma("unroll") for (int ai = 0; ai < 2; ++ai) _Pragma("unroll") for (int m = 0; m < 4; ++m) _Pragma("unroll") for (int bj = 0; bj < 2; ++bj) { \
;         const int row = u.pm * 256 + ai * 128 + wr * 64 + m * 16 + fr, col = u.pn * 256 + bj * 128 + wc * 32 + 8 * fq; const f32x4 v0 = acc[ai][bj][m][0], v1 = acc[ai][bj][m][1]; (void)row; (void)col; __VA_ARGS__ }
;     __device__ __forceinline__ void pre_issue(const pg8::Unit& u, int tid, f32x4& v) const {
;         if (tid < 256) v = *(const f32x4*)(ss + ((size_t)u.pm * 256 + tid) * 4);
;         else v[0] = cf[(size_t)(u.pm < 64 ? (u.pm >> 3) : 8) * DFF + u.pn * 256 + (tid - 256)]; }
;     __device__ __forceinline__ void pre_commit(int tid, int par, const f32x4& v) const {
;         red[par * 512 + tid] = tid < 256 ? rsqrtf((v[0] + v[1] + v[2] + v[3]) * (1.f / DM) + EPS) : v[0]; }
;     __device__ __forceinline__ void operator()(const f32x4 (&acc)[2][2][4][2], const pg8::Unit& u, int wr, int wc, int fr, int fq, int par) const {
;         const LAS float* rp = red + par * 512 + wr * 64 + fr; const LAS float* cp = rp - (wr * 64 + fr) + 256 + wc * 32 + 8 * fq;
;         EPI_FOREACH( const f32x4 c0 = *(const LAS f32x4*)(cp + bj * 128), c1 = *(const LAS f32x4*)(cp + bj * 128 + 4); const float r = rp[ai * 128 + m * 16]; f32x4 a, b;
;             _Pragma("unroll") for (int q = 0; q < 4; ++q) { const float ra = fmaxf(v0[q] * r + c0[q], 0.f), rb = fmaxf(v1[q] * r + c1[q], 0.f); a[q] = ra * ra; b[q] = rb * rb; }
;             *(pg8::u32x4*)(O + (size_t)row * DFF + col) = pack8(a, b); )
;     }
	v_pk_mul_f32 v[202:203], v[202:203], v[202:203]
	v_pk_mul_f32 v[204:205], v[204:205], v[204:205]
	v_cvt_pk_bf16_f32 v218, v198, v199
	v_cvt_pk_bf16_f32 v219, v200, v201
	v_cvt_pk_bf16_f32 v220, v202, v203
	v_cvt_pk_bf16_f32 v221, v204, v205
	global_store_dwordx4 v229, v[218:221], s[98:99]
	v_pk_fma_f32 v[206:207], v[30:31], v[192:193], v[174:175] op_sel_hi:[1,0,1]
	v_pk_fma_f32 v[208:209], v[32:33], v[192:193], v[176:177] op_sel_hi:[1,0,1]
	v_pk_fma_f32 v[210:211], v[26:27], v[192:193], v[178:179] op_sel_hi:[1,0,1]
	v_pk_fma_f32 v[212:213], v[28:29], v[192:193], v[180:181] op_sel_hi:[1,0,1]
	v_max_f32_e32 v206, 0, v206
	v_max_f32_e32 v207, 0, v207
	v_max_f32_e32 v208, 0, v208
	v_max_f32_e32 v209, 0, v209
	v_max_f32_e32 v210, 0, v210
	v_max_f32_e32 v211, 0, v211
	v_max_f32_e32 v212, 0, v212
	v_max_f32_e32 v213, 0, v213
	v_pk_mul_f32 v[206:207], v[206:207], v[206:207]
	v_pk_mul_f32 v[208:209], v[208:209], v[208:209]
	v_pk_mul_f32 v[210:211], v[210:211], v[210:211]
	v_pk_mul_f32 v[212:213], v[212:213], v[212:213]
	v_cvt_pk_bf16_f32 v222, v206, v207
	v_cvt_pk_bf16_f32 v223, v208, v209
	v_cvt_pk_bf16_f32 v224, v210, v211
	v_cvt_pk_bf16_f32 v225, v212, v213
	global_store_dwordx4 v229, v[222:225], s[98:99] offset:256
	s_add_u32 s98, s98, 0x20000
	s_addc_u32 s99, s99, 0
	v_pk_fma_f32 v[198:199], v[54:55], v[194:195], v[166:167] op_sel_hi:[1,0,1]
	v_pk_fma_f32 v[200:201], v[56:57], v[194:195], v[168:169] op_sel_hi:[1,0,1]
	v_pk_fma_f32 v[202:203], v[50:51], v[194:195], v[170:171] op_sel_hi:[1,0,1]
	v_pk_fma_f32 v[204:205], v[52:53], v[194:195], v[172:173] op_sel_hi:[1,0,1]
	v_max_f32_e32 v198, 0, v198
	v_max_f32_e32 v199, 0, v199
	v_max_f32_e32 v200, 0, v200
	v_max_f32_e32 v201, 0, v201
	v_max_f32_e32 v202, 0, v202
	v_max_f32_e32 v203, 0, v203
	v_max_f32_e32 v204, 0, v204
	v_max_f32_e32 v205, 0, v205
	v_pk_mul_f32 v[198:199], v[198:199], v[198:199]
	v_pk_mul_f32 v[200:201], v[200:201], v[200:201]
	v_pk_mul_f32 v[202:203], v[202:203], v[202:203]
	v_pk_mul_f32 v[204:205], v[204:205], v[204:205]
	v_cvt_pk_bf16_f32 v214, v198, v199
	v_cvt_pk_bf16_f32 v215, v200, v201
	v_cvt_pk_bf16_f32 v216, v202, v203
	v_cvt_pk_bf16_f32 v217, v204, v205
	global_store_dwordx4 v229, v[214:217], s[98:99]
	v_pk_fma_f32 v[206:207], v[22:23], v[194:195], v[174:175] op_sel_hi:[1,0,1]
	v_pk_fma_f32 v[208:209], v[24:25], v[194:195], v[176:177] op_sel_hi:[1,0,1]
	v_pk_fma_f32 v[210:211], v[18:19], v[194:195], v[178:179] op_sel_hi:[1,0,1]
	v_pk_fma_f32 v[212:213], v[20:21], v[194:195], v[180:181] op_sel_hi:[1,0,1]
	v_max_f32_e32 v206, 0, v206
	v_max_f32_e32 v207, 0, v207
	v_max_f32_e32 v208, 0, v208
	v_max_f32_e32 v209, 0, v209
	v_max_f32_e32 v210, 0, v210
	v_max_f32_e32 v211, 0, v211
	v_max_f32_e32 v212, 0, v212
	v_max_f32_e32 v213, 0, v213
	v_pk_mul_f32 v[206:207], v[206:207], v[206:207]
	v_pk_mul_f32 v[208:209], v[208:209], v[208:209]
	v_pk_mul_f32 v[210:211], v[210:211], v[210:211]
	v_pk_mul_f32 v[212:213], v[212:213], v[212:213]
	v_cvt_pk_bf16_f32 v218, v206, v207
	v_cvt_pk_bf16_f32 v219, v208, v209
	v_cvt_pk_bf16_f32 v220, v210, v211
	v_cvt_pk_bf16_f32 v221, v212, v213
	global_store_dwordx4 v229, v[218:221], s[98:99] offset:256
	s_add_u32 s98, s98, 0x20000
	s_addc_u32 s99, s99, 0
	v_pk_fma_f32 v[198:199], v[46:47], v[196:197], v[166:167] op_sel_hi:[1,0,1]
	v_pk_fma_f32 v[200:201], v[48:49], v[196:197], v[168:169] op_sel_hi:[1,0,1]
	v_pk_fma_f32 v[202:203], v[42:43], v[196:197], v[170:171] op_sel_hi:[1,0,1]
	v_pk_fma_f32 v[204:205], v[44:45], v[196:197], v[172:173] op_sel_hi:[1,0,1]
	v_max_f32_e32 v198, 0, v198
	v_max_f32_e32 v199, 0, v199
	v_max_f32_e32 v200, 0, v200
	v_max_f32_e32 v201, 0, v201
	v_max_f32_e32 v202, 0, v202
	v_max_f32_e32 v203, 0, v203
	v_max_f32_e32 v204, 0, v204
	v_max_f32_e32 v205, 0, v205
	v_pk_mul_f32 v[198:199], v[198:199], v[198:199]
	v_pk_mul_f32 v[200:201], v[200:201], v[200:201]
	v_pk_mul_f32 v[202:203], v[202:203], v[202:203]
	v_pk_mul_f32 v[204:205], v[204:205], v[204:205]
	v_cvt_pk_bf16_f32 v222, v198, v199
	v_cvt_pk_bf16_f32 v223, v200, v201
	v_cvt_pk_bf16_f32 v224, v202, v203
	v_cvt_pk_bf16_f32 v225, v204, v205
	global_store_dwordx4 v229, v[222:225], s[98:99]
	v_pk_fma_f32 v[206:207], v[14:15], v[196:197], v[174:175] op_sel_hi:[1,0,1]
	v_pk_fma_f32 v[208:209], v[16:17], v[196:197], v[176:177] op_sel_hi:[1,0,1]
	v_pk_fma_f32 v[210:211], v[10:11], v[196:197], v[178:179] op_sel_hi:[1,0,1]
	v_pk_fma_f32 v[212:213], v[12:13], v[196:197], v[180:181] op_sel_hi:[1,0,1]
	v_max_f32_e32 v206, 0, v206
	v_max_f32_e32 v207, 0, v207
	v_max_f32_e32 v208, 0, v208
	v_max_f32_e32 v209, 0, v209
	v_max_f32_e32 v210, 0, v210
	v_max_f32_e32 v211, 0, v211
	v_max_f32_e32 v212, 0, v212
	v_max_f32_e32 v213, 0, v213
	v_pk_mul_f32 v[206:207], v[206:207], v[206:207]
	v_pk_mul_f32 v[208:209], v[208:209], v[208:209]
	v_pk_mul_f32 v[210:211], v[210:211], v[210:211]
	v_pk_mul_f32 v[212:213], v[212:213], v[212:213]
	v_cvt_pk_bf16_f32 v214, v206, v207
	v_cvt_pk_bf16_f32 v215, v208, v209
	v_cvt_pk_bf16_f32 v216, v210, v211
	v_cvt_pk_bf16_f32 v217, v212, v213
	global_store_dwordx4 v229, v[214:217], s[98:99] offset:256
	s_and_b64 vcc, exec, s[12:13]
	s_cbranch_vccnz .LBB0_3343
	s_waitcnt vmcnt(0)
	v_mov_b32_e32 v6, v2
	s_and_saveexec_b64 s[10:11], s[4:5]
	s_cbranch_execz .LBB0_3341
	v_add_f32_e32 v6, v2, v3
	v_add_f32_e32 v6, v4, v6
	v_add_f32_e32 v6, v5, v6
	v_fmamk_f32 v6, v6, 0x3a800000, v165
	v_mul_f32_e32 v7, 0x4b800000, v6
	v_cmp_gt_f32_e32 vcc, s65, v6
	s_nop 1
	v_cndmask_b32_e32 v6, v6, v7, vcc
	v_rsq_f32_e32 v6, v6
	s_nop 0
	v_mul_f32_e32 v7, 0x45800000, v6
	v_cndmask_b32_e32 v6, v6, v7, vcc
